# merges the paired vmcnt/lgkmcnt waits of each GEMM load segment into one s_waitcnt and drops the redundant loop-top lgkmcnt wait
# baseline (speedup 1.0000x reference)
; #define PG8_STAGE(bufoff, gbase, voff) do { _Pragma("unroll") for (int _i = 0; _i < 2; ++_i) \
;         __builtin_amdgcn_global_load_lds((const unsigned*)((const char*)(gbase) + (voff)[_i]), (LAS unsigned*)(lds + (bufoff) + ldsw + _i * 8192), 16, 0, 0); } while (0)
; #define PG8_LDA(dst, b, h) do { _Pragma("unroll") for (int m = 0; m < 4; ++m) _Pragma("unroll") for (int k = 0; k < 2; ++k) dst[m][k] = *(const LAS bf16x8*)(lds + PG8_SA(b, h) + aoff + m * 2048 + k * 1024); } while (0)
; #define PG8_LDB(dst, b, h) do { _Pragma("unroll") for (int n = 0; n < 2; ++n) _Pragma("unroll") for (int k = 0; k < 2; ++k) dst[n][k] = *(const LAS bf16x8*)(lds + PG8_SB(b, h) + boff + n * 2048 + k * 1024); } while (0)
; #define PG8_MMA(ai, bj, At, Bt) do { __builtin_amdgcn_s_setprio(1); _Pragma("unroll") for (int m = 0; m < 4; ++m) _Pragma("unroll") for (int n = 0; n < 2; ++n) _Pragma("unroll") for (int k = 0; k < 2; ++k) \
;         acc[ai][bj][m][n] = __builtin_amdgcn_mfma_f32_16x16x32_bf16(Bt[n][k], At[m][k], acc[ai][bj][m][n], 0, 0, 0); __builtin_amdgcn_s_setprio(0); } while (0)
; #define PG8_WAIT_V(n) asm volatile("s_waitcnt vmcnt(" #n ")" ::: "memory")
; #define PG8_WAIT_L(n) asm volatile("s_waitcnt lgkmcnt(" #n ")" ::: "memory")
; #define PG8_BAR __builtin_amdgcn_s_barrier()
; #define PG8_SCHED __builtin_amdgcn_sched_barrier(0)
; __device__ __forceinline__ void gemm_phase(LAS unsigned char* lds, const Gemm g, const StaticOrder& S, const Epi& E) {
;     ...
;             PG8_LDB(B0, 0, 0); PG8_LDB(B1, 0, 1); PG8_SCHED; PG8_LDA(At, 0, 0); PG8_STAGE(PG8_SA(1, 1), a1 + hstepA, voffA);
;             PG8_WAIT_V(8); PG8_WAIT_L(0); PG8_BAR; PG8_MMA(0, 0, At, B0); PG8_MMA(0, 1, At, B1); PG8_BAR; PG8_SCHED;
;             PG8_LDA(At, 0, 1); PG8_STAGE(PG8_SB(0, 0), b2, voffB); PG8_STAGE(PG8_SB(0, 1), b2 + hstepB, voffB); PG8_STAGE(PG8_SA(0, 0), a2, voffA);
;             PG8_WAIT_V(8); PG8_WAIT_L(0); PG8_BAR; PG8_MMA(1, 0, At, B0); PG8_MMA(1, 1, At, B1); PG8_BAR; PG8_SCHED;
.LBB0_177:
	ds_read_b128 v[130:133], v226
	ds_read_b128 v[134:137], v226 offset:1024
	ds_read_b128 v[138:141], v226 offset:2048
	ds_read_b128 v[142:145], v226 offset:3072
	ds_read_b128 v[146:149], v227
	ds_read_b128 v[150:153], v227 offset:1024
	ds_read_b128 v[154:157], v227 offset:2048
	ds_read_b128 v[182:185], v227 offset:3072
	s_add_i32 s27, s17, 2
	s_add_u32 s2, s0, 0x80
	s_addc_u32 s3, s1, 0
	s_cmp_eq_u32 s85, s17
	s_cselect_b32 s3, s7, s3
	s_cselect_b32 s2, s6, s2
	s_cselect_b32 s41, s95, s16
	s_cselect_b32 s40, s94, s5
	s_add_i32 m0, s71, 0xc000
	ds_read_b128 v[186:189], v217
	ds_read_b128 v[190:193], v217 offset:1024
	ds_read_b128 v[194:197], v217 offset:2048
	ds_read_b128 v[198:201], v217 offset:3072
	ds_read_b128 v[202:205], v217 offset:4096
	ds_read_b128 v[206:209], v217 offset:5120
	ds_read_b128 v[218:221], v217 offset:6144
	ds_read_b128 v[222:225], v217 offset:7168
	global_load_lds_dwordx4 v178, s[0:1]
	s_add_i32 m0, s71, 0xe000
	s_nop 0
	global_load_lds_dwordx4 v180, s[0:1]
	s_waitcnt vmcnt(8) lgkmcnt(0)
	s_barrier
	s_setprio 1
	v_mfma_f32_16x16x32_bf16 v[114:117], v[130:133], v[186:189], v[114:117]
	v_mfma_f32_16x16x32_bf16 v[126:129], v[138:141], v[186:189], v[126:129]
	v_mfma_f32_16x16x32_bf16 v[110:113], v[130:133], v[194:197], v[110:113]
	v_mfma_f32_16x16x32_bf16 v[102:105], v[138:141], v[194:197], v[102:105]
	v_mfma_f32_16x16x32_bf16 v[94:97], v[130:133], v[202:205], v[94:97]
	v_mfma_f32_16x16x32_bf16 v[86:89], v[138:141], v[202:205], v[86:89]
	v_mfma_f32_16x16x32_bf16 v[78:81], v[130:133], v[218:221], v[78:81]
	v_mfma_f32_16x16x32_bf16 v[70:73], v[138:141], v[218:221], v[70:73]
	v_mfma_f32_16x16x32_bf16 v[114:117], v[134:137], v[190:193], v[114:117]
	v_mfma_f32_16x16x32_bf16 v[126:129], v[142:145], v[190:193], v[126:129]
	v_mfma_f32_16x16x32_bf16 v[110:113], v[134:137], v[198:201], v[110:113]
	v_mfma_f32_16x16x32_bf16 v[102:105], v[142:145], v[198:201], v[102:105]
	v_mfma_f32_16x16x32_bf16 v[94:97], v[134:137], v[206:209], v[94:97]
	v_mfma_f32_16x16x32_bf16 v[86:89], v[142:145], v[206:209], v[86:89]
	v_mfma_f32_16x16x32_bf16 v[78:81], v[134:137], v[222:225], v[78:81]
	v_mfma_f32_16x16x32_bf16 v[70:73], v[142:145], v[222:225], v[70:73]
	v_mfma_f32_16x16x32_bf16 v[122:125], v[146:149], v[186:189], v[122:125]
	v_mfma_f32_16x16x32_bf16 v[118:121], v[154:157], v[186:189], v[118:121]
	v_mfma_f32_16x16x32_bf16 v[106:109], v[146:149], v[194:197], v[106:109]
	v_mfma_f32_16x16x32_bf16 v[98:101], v[154:157], v[194:197], v[98:101]
	v_mfma_f32_16x16x32_bf16 v[90:93], v[146:149], v[202:205], v[90:93]
	v_mfma_f32_16x16x32_bf16 v[82:85], v[154:157], v[202:205], v[82:85]
	v_mfma_f32_16x16x32_bf16 v[74:77], v[146:149], v[218:221], v[74:77]
	v_mfma_f32_16x16x32_bf16 v[66:69], v[154:157], v[218:221], v[66:69]
	v_mfma_f32_16x16x32_bf16 v[122:125], v[150:153], v[190:193], v[122:125]
	v_mfma_f32_16x16x32_bf16 v[118:121], v[182:185], v[190:193], v[118:121]
	v_mfma_f32_16x16x32_bf16 v[106:109], v[150:153], v[198:201], v[106:109]
	v_mfma_f32_16x16x32_bf16 v[98:101], v[182:185], v[198:201], v[98:101]
	v_mfma_f32_16x16x32_bf16 v[90:93], v[150:153], v[206:209], v[90:93]
	v_mfma_f32_16x16x32_bf16 v[82:85], v[182:185], v[206:209], v[82:85]
	v_mfma_f32_16x16x32_bf16 v[74:77], v[150:153], v[222:225], v[74:77]
	v_mfma_f32_16x16x32_bf16 v[66:69], v[182:185], v[222:225], v[66:69]
	s_setprio 0
	s_barrier
	s_add_i32 s17, s39, s70
	s_mov_b32 m0, s17
	ds_read_b128 v[186:189], v217 offset:16384
	ds_read_b128 v[190:193], v217 offset:17408
	ds_read_b128 v[194:197], v217 offset:18432
	ds_read_b128 v[198:201], v217 offset:19456
	ds_read_b128 v[202:205], v217 offset:20480
	ds_read_b128 v[206:209], v217 offset:21504
	ds_read_b128 v[218:221], v217 offset:22528
	ds_read_b128 v[222:225], v217 offset:23552
	global_load_lds_dwordx4 v160, s[40:41]
	s_add_i32 m0, s17, 0x2000
	s_add_i32 s17, s24, s70
	global_load_lds_dwordx4 v164, s[40:41]
	s_add_u32 s40, s40, s52
	s_addc_u32 s41, s41, s53
	s_mov_b32 m0, s17
	s_nop 0
	global_load_lds_dwordx4 v160, s[40:41]
	s_add_i32 m0, s17, 0x2000
	s_nop 0
	global_load_lds_dwordx4 v164, s[40:41]
	s_mov_b32 m0, s71
	s_nop 0
	global_load_lds_dwordx4 v158, s[2:3]
	s_mov_b32 m0, s34
	s_nop 0
	global_load_lds_dwordx4 v162, s[2:3]
	s_waitcnt vmcnt(8) lgkmcnt(0)
	s_barrier
	s_setprio 1
	v_mfma_f32_16x16x32_bf16 v[62:65], v[130:133], v[186:189], v[62:65]
	v_mfma_f32_16x16x32_bf16 v[54:57], v[138:141], v[186:189], v[54:57]
	v_mfma_f32_16x16x32_bf16 v[46:49], v[130:133], v[194:197], v[46:49]
	v_mfma_f32_16x16x32_bf16 v[38:41], v[138:141], v[194:197], v[38:41]
	v_mfma_f32_16x16x32_bf16 v[30:33], v[130:133], v[202:205], v[30:33]
	v_mfma_f32_16x16x32_bf16 v[22:25], v[138:141], v[202:205], v[22:25]
	v_mfma_f32_16x16x32_bf16 v[14:17], v[130:133], v[218:221], v[14:17]
	v_mfma_f32_16x16x32_bf16 v[6:9], v[138:141], v[218:221], v[6:9]
	v_mfma_f32_16x16x32_bf16 v[62:65], v[134:137], v[190:193], v[62:65]
	v_mfma_f32_16x16x32_bf16 v[54:57], v[142:145], v[190:193], v[54:57]
	v_mfma_f32_16x16x32_bf16 v[46:49], v[134:137], v[198:201], v[46:49]
	v_mfma_f32_16x16x32_bf16 v[38:41], v[142:145], v[198:201], v[38:41]
	v_mfma_f32_16x16x32_bf16 v[30:33], v[134:137], v[206:209], v[30:33]
	v_mfma_f32_16x16x32_bf16 v[22:25], v[142:145], v[206:209], v[22:25]
	v_mfma_f32_16x16x32_bf16 v[14:17], v[134:137], v[222:225], v[14:17]
	v_mfma_f32_16x16x32_bf16 v[6:9], v[142:145], v[222:225], v[6:9]
	v_mfma_f32_16x16x32_bf16 v[58:61], v[146:149], v[186:189], v[58:61]
	v_mfma_f32_16x16x32_bf16 v[50:53], v[154:157], v[186:189], v[50:53]
	v_mfma_f32_16x16x32_bf16 v[42:45], v[146:149], v[194:197], v[42:45]
	v_mfma_f32_16x16x32_bf16 v[34:37], v[154:157], v[194:197], v[34:37]
	v_mfma_f32_16x16x32_bf16 v[26:29], v[146:149], v[202:205], v[26:29]
	v_mfma_f32_16x16x32_bf16 v[18:21], v[154:157], v[202:205], v[18:21]
	v_mfma_f32_16x16x32_bf16 v[10:13], v[146:149], v[218:221], v[10:13]
	v_mfma_f32_16x16x32_bf16 v[2:5], v[154:157], v[218:221], v[2:5]
	v_mfma_f32_16x16x32_bf16 v[58:61], v[150:153], v[190:193], v[58:61]
	v_mfma_f32_16x16x32_bf16 v[50:53], v[182:185], v[190:193], v[50:53]
	v_mfma_f32_16x16x32_bf16 v[42:45], v[150:153], v[198:201], v[42:45]
	v_mfma_f32_16x16x32_bf16 v[34:37], v[182:185], v[198:201], v[34:37]
	v_mfma_f32_16x16x32_bf16 v[26:29], v[150:153], v[206:209], v[26:29]
	v_mfma_f32_16x16x32_bf16 v[18:21], v[182:185], v[206:209], v[18:21]
	v_mfma_f32_16x16x32_bf16 v[10:13], v[150:153], v[222:225], v[10:13]
	v_mfma_f32_16x16x32_bf16 v[2:5], v[182:185], v[222:225], v[2:5]
	s_setprio 0
	s_barrier
; #define PG8_STAGE(bufoff, gbase, voff) do { _Pragma("unroll") for (int _i = 0; _i < 2; ++_i) \
;         __builtin_amdgcn_global_load_lds((const unsigned*)((const char*)(gbase) + (voff)[_i]), (LAS unsigned*)(lds + (bufoff) + ldsw + _i * 8192), 16, 0, 0); } while (0)
; #define PG8_LDA(dst, b, h) do { _Pragma("unroll") for (int m = 0; m < 4; ++m) _Pragma("unroll") for (int k = 0; k < 2; ++k) dst[m][k] = *(const LAS bf16x8*)(lds + PG8_SA(b, h) + aoff + m * 2048 + k * 1024); } while (0)
; #define PG8_LDB(dst, b, h) do { _Pragma("unroll") for (int n = 0; n < 2; ++n) _Pragma("unroll") for (int k = 0; k < 2; ++k) dst[n][k] = *(const LAS bf16x8*)(lds + PG8_SB(b, h) + boff + n * 2048 + k * 1024); } while (0)
; #define PG8_MMA(ai, bj, At, Bt) do { __builtin_amdgcn_s_setprio(1); _Pragma("unroll") for (int m = 0; m < 4; ++m) _Pragma("unroll") for (int n = 0; n < 2; ++n) _Pragma("unroll") for (int k = 0; k < 2; ++k) \
;         acc[ai][bj][m][n] = __builtin_amdgcn_mfma_f32_16x16x32_bf16(Bt[n][k], At[m][k], acc[ai][bj][m][n], 0, 0, 0); __builtin_amdgcn_s_setprio(0); } while (0)
; #define PG8_WAIT_V(n) asm volatile("s_waitcnt vmcnt(" #n ")" ::: "memory")
; #define PG8_WAIT_L(n) asm volatile("s_waitcnt lgkmcnt(" #n ")" ::: "memory")
; #define PG8_BAR __builtin_amdgcn_s_barrier()
; #define PG8_SCHED __builtin_amdgcn_sched_barrier(0)
; __device__ __forceinline__ void gemm_phase(LAS unsigned char* lds, const Gemm g, const StaticOrder& S, const Epi& E) {
;     ...
;             PG8_LDB(B0, 1, 0); PG8_LDB(B1, 1, 1); PG8_SCHED; PG8_LDA(At, 1, 0); PG8_STAGE(PG8_SA(0, 1), a2 + hstepA, voffA);
;             PG8_WAIT_V(8); PG8_WAIT_L(0); PG8_BAR; PG8_MMA(0, 0, At, B0); PG8_MMA(0, 1, At, B1); PG8_BAR; PG8_SCHED;
;             PG8_LDA(At, 1, 1); PG8_STAGE(PG8_SB(1, 0), b3, voffB); PG8_STAGE(PG8_SB(1, 1), b3 + hstepB, voffB); PG8_STAGE(PG8_SA(1, 0), a3, voffA);
;             PG8_WAIT_V(8); PG8_WAIT_L(0); PG8_BAR; PG8_MMA(1, 0, At, B0); PG8_MMA(1, 1, At, B1); PG8_BAR; PG8_SCHED;
	ds_read_b128 v[130:133], v228
	ds_read_b128 v[134:137], v228 offset:1024
	ds_read_b128 v[138:141], v228 offset:2048
	ds_read_b128 v[142:145], v228 offset:3072
	ds_read_b128 v[146:149], v229
	ds_read_b128 v[150:153], v229 offset:1024
	ds_read_b128 v[154:157], v229 offset:2048
	ds_read_b128 v[182:185], v229 offset:3072
	s_add_u32 s2, s2, s50
	s_addc_u32 s3, s3, s51
	s_mov_b32 m0, s92
	ds_read_b128 v[186:189], v217 offset:32768
	ds_read_b128 v[190:193], v217 offset:33792
	ds_read_b128 v[194:197], v217 offset:34816
	ds_read_b128 v[198:201], v217 offset:35840
	ds_read_b128 v[202:205], v217 offset:36864
	ds_read_b128 v[206:209], v217 offset:37888
	ds_read_b128 v[218:221], v217 offset:38912
	ds_read_b128 v[222:225], v217 offset:39936
	global_load_lds_dwordx4 v158, s[2:3]
	s_mov_b32 m0, s93
	s_nop 0
	global_load_lds_dwordx4 v162, s[2:3]
	s_waitcnt vmcnt(8) lgkmcnt(0)
	s_barrier
	s_setprio 1
	v_mfma_f32_16x16x32_bf16 v[114:117], v[130:133], v[186:189], v[114:117]
	v_mfma_f32_16x16x32_bf16 v[126:129], v[138:141], v[186:189], v[126:129]
	v_mfma_f32_16x16x32_bf16 v[110:113], v[130:133], v[194:197], v[110:113]
	v_mfma_f32_16x16x32_bf16 v[102:105], v[138:141], v[194:197], v[102:105]
	v_mfma_f32_16x16x32_bf16 v[94:97], v[130:133], v[202:205], v[94:97]
	v_mfma_f32_16x16x32_bf16 v[86:89], v[138:141], v[202:205], v[86:89]
	v_mfma_f32_16x16x32_bf16 v[78:81], v[130:133], v[218:221], v[78:81]
	v_mfma_f32_16x16x32_bf16 v[70:73], v[138:141], v[218:221], v[70:73]
	v_mfma_f32_16x16x32_bf16 v[114:117], v[134:137], v[190:193], v[114:117]
	v_mfma_f32_16x16x32_bf16 v[126:129], v[142:145], v[190:193], v[126:129]
	v_mfma_f32_16x16x32_bf16 v[110:113], v[134:137], v[198:201], v[110:113]
	v_mfma_f32_16x16x32_bf16 v[102:105], v[142:145], v[198:201], v[102:105]
	v_mfma_f32_16x16x32_bf16 v[94:97], v[134:137], v[206:209], v[94:97]
	v_mfma_f32_16x16x32_bf16 v[86:89], v[142:145], v[206:209], v[86:89]
	v_mfma_f32_16x16x32_bf16 v[78:81], v[134:137], v[222:225], v[78:81]
	v_mfma_f32_16x16x32_bf16 v[70:73], v[142:145], v[222:225], v[70:73]
	v_mfma_f32_16x16x32_bf16 v[122:125], v[146:149], v[186:189], v[122:125]
	v_mfma_f32_16x16x32_bf16 v[118:121], v[154:157], v[186:189], v[118:121]
	v_mfma_f32_16x16x32_bf16 v[106:109], v[146:149], v[194:197], v[106:109]
	v_mfma_f32_16x16x32_bf16 v[98:101], v[154:157], v[194:197], v[98:101]
	v_mfma_f32_16x16x32_bf16 v[90:93], v[146:149], v[202:205], v[90:93]
	v_mfma_f32_16x16x32_bf16 v[82:85], v[154:157], v[202:205], v[82:85]
	v_mfma_f32_16x16x32_bf16 v[74:77], v[146:149], v[218:221], v[74:77]
	v_mfma_f32_16x16x32_bf16 v[66:69], v[154:157], v[218:221], v[66:69]
	v_mfma_f32_16x16x32_bf16 v[122:125], v[150:153], v[190:193], v[122:125]
	v_mfma_f32_16x16x32_bf16 v[118:121], v[182:185], v[190:193], v[118:121]
	v_mfma_f32_16x16x32_bf16 v[106:109], v[150:153], v[198:201], v[106:109]
	v_mfma_f32_16x16x32_bf16 v[98:101], v[182:185], v[198:201], v[98:101]
	v_mfma_f32_16x16x32_bf16 v[90:93], v[150:153], v[206:209], v[90:93]
	v_mfma_f32_16x16x32_bf16 v[82:85], v[182:185], v[206:209], v[82:85]
	v_mfma_f32_16x16x32_bf16 v[74:77], v[150:153], v[222:225], v[74:77]
	v_mfma_f32_16x16x32_bf16 v[66:69], v[182:185], v[222:225], v[66:69]
	s_setprio 0
	s_barrier
	s_add_u32 s40, s40, 0x80
	s_addc_u32 s41, s41, 0
	s_sub_u32 s100, s40, s52
	s_subb_u32 s101, s41, s53
	s_sub_u32 s2, s2, s50
	s_subb_u32 s3, s3, s51
	s_add_u32 s2, s2, 0x80
	s_addc_u32 s3, s3, 0
	s_add_i32 vcc_lo, s25, s70
	s_mov_b32 m0, vcc_lo
	ds_read_b128 v[186:189], v217 offset:49152
	ds_read_b128 v[190:193], v217 offset:50176
	ds_read_b128 v[194:197], v217 offset:51200
	ds_read_b128 v[198:201], v217 offset:52224
	ds_read_b128 v[202:205], v217 offset:53248
	ds_read_b128 v[206:209], v217 offset:54272
	ds_read_b128 v[218:221], v217 offset:55296
	ds_read_b128 v[222:225], v217 offset:56320
	global_load_lds_dwordx4 v160, s[100:101]
	s_add_i32 m0, vcc_lo, 0x2000
	s_add_i32 vcc_lo, s26, s70
	global_load_lds_dwordx4 v164, s[100:101]
	s_mov_b32 m0, vcc_lo
	s_nop 0
	global_load_lds_dwordx4 v160, s[40:41]
	s_add_i32 m0, vcc_lo, 0x2000
	s_nop 0
	global_load_lds_dwordx4 v164, s[40:41]
	s_mov_b32 m0, s58
	s_nop 0
	global_load_lds_dwordx4 v158, s[2:3]
	s_mov_b32 m0, s59
	s_nop 0
	global_load_lds_dwordx4 v162, s[2:3]
	s_waitcnt vmcnt(8) lgkmcnt(0)
	s_barrier
	s_setprio 1
	v_mfma_f32_16x16x32_bf16 v[62:65], v[130:133], v[186:189], v[62:65]
	v_mfma_f32_16x16x32_bf16 v[54:57], v[138:141], v[186:189], v[54:57]
	v_mfma_f32_16x16x32_bf16 v[46:49], v[130:133], v[194:197], v[46:49]
	v_mfma_f32_16x16x32_bf16 v[38:41], v[138:141], v[194:197], v[38:41]
	v_mfma_f32_16x16x32_bf16 v[30:33], v[130:133], v[202:205], v[30:33]
	v_mfma_f32_16x16x32_bf16 v[22:25], v[138:141], v[202:205], v[22:25]
	v_mfma_f32_16x16x32_bf16 v[14:17], v[130:133], v[218:221], v[14:17]
	v_mfma_f32_16x16x32_bf16 v[6:9], v[138:141], v[218:221], v[6:9]
	v_mfma_f32_16x16x32_bf16 v[62:65], v[134:137], v[190:193], v[62:65]
	v_mfma_f32_16x16x32_bf16 v[54:57], v[142:145], v[190:193], v[54:57]
	v_mfma_f32_16x16x32_bf16 v[46:49], v[134:137], v[198:201], v[46:49]
	v_mfma_f32_16x16x32_bf16 v[38:41], v[142:145], v[198:201], v[38:41]
	v_mfma_f32_16x16x32_bf16 v[30:33], v[134:137], v[206:209], v[30:33]
	v_mfma_f32_16x16x32_bf16 v[22:25], v[142:145], v[206:209], v[22:25]
	v_mfma_f32_16x16x32_bf16 v[14:17], v[134:137], v[222:225], v[14:17]
	v_mfma_f32_16x16x32_bf16 v[6:9], v[142:145], v[222:225], v[6:9]
	v_mfma_f32_16x16x32_bf16 v[58:61], v[146:149], v[186:189], v[58:61]
	v_mfma_f32_16x16x32_bf16 v[50:53], v[154:157], v[186:189], v[50:53]
	v_mfma_f32_16x16x32_bf16 v[42:45], v[146:149], v[194:197], v[42:45]
	v_mfma_f32_16x16x32_bf16 v[34:37], v[154:157], v[194:197], v[34:37]
	v_mfma_f32_16x16x32_bf16 v[26:29], v[146:149], v[202:205], v[26:29]
	v_mfma_f32_16x16x32_bf16 v[18:21], v[154:157], v[202:205], v[18:21]
	v_mfma_f32_16x16x32_bf16 v[10:13], v[146:149], v[218:221], v[10:13]
	v_mfma_f32_16x16x32_bf16 v[2:5], v[154:157], v[218:221], v[2:5]
	v_mfma_f32_16x16x32_bf16 v[58:61], v[150:153], v[190:193], v[58:61]
	v_mfma_f32_16x16x32_bf16 v[50:53], v[182:185], v[190:193], v[50:53]
	v_mfma_f32_16x16x32_bf16 v[42:45], v[150:153], v[198:201], v[42:45]
	v_mfma_f32_16x16x32_bf16 v[34:37], v[182:185], v[198:201], v[34:37]
	v_mfma_f32_16x16x32_bf16 v[26:29], v[150:153], v[206:209], v[26:29]
	v_mfma_f32_16x16x32_bf16 v[18:21], v[182:185], v[206:209], v[18:21]
	v_mfma_f32_16x16x32_bf16 v[10:13], v[150:153], v[222:225], v[10:13]
	v_mfma_f32_16x16x32_bf16 v[2:5], v[182:185], v[222:225], v[2:5]
	s_setprio 0
	s_barrier
	s_add_u32 s0, s0, 0x100
	s_addc_u32 s1, s1, 0
	s_add_u32 s5, s5, 0x100
	s_addc_u32 s16, s16, 0
	s_cmp_ge_i32 s27, s84
	s_mov_b32 s17, s27
	s_cbranch_scc0 .LBB0_177
	s_and_b64 vcc, exec, s[74:75]
	s_cbranch_vccz .LBB0_180
